# GEMM mainloop heads aligned to 128-byte boundaries instead of 64; otherwise v19
# baseline (speedup 1.0000x reference)
; #define PG8_STAGE(bufoff, gbase, voff) do { _Pragma("unroll") for (int _i = 0; _i < 2; ++_i) \
;     __builtin_amdgcn_global_load_lds((const unsigned*)((const char*)(gbase) + (voff)[_i]), (LAS unsigned*)(lds + (bufoff) + ldsw + _i * 8192), 16, 0, 0); } while (0)
; #define PG8_WAIT_V(n) asm volatile("s_waitcnt vmcnt(" #n ")" ::: "memory")
; #define PG8_BAR __builtin_amdgcn_s_barrier()
; template <class Epi>
; DI void gemm_phase(LAS unsigned char* lds, const Gemm g, const StaticOrder& S, const Epi& E) {
;     ...
;   Unit cur, nxt; int ui = 0;
;   if (!S.next(0, cur)) return;
;   f32x4 acc[2][2][4][2];
; #pragma unroll
;   for (int a = 0; a < 2; ++a)
; #pragma unroll
;     for (int b = 0; b < 2; ++b)
; #pragma unroll
;       for (int m = 0; m < 4; ++m)
; #pragma unroll
;         for (int n = 0; n < 2; ++n) acc[a][b][m][n] = (f32x4){0.f, 0.f, 0.f, 0.f};
;   bf16x8 At[4][2], B0[2][2], B1[2][2];
;   const char* cA = PG8_UA(cur); const char* cB = PG8_UB(cur);
;   PG8_STAGE(PG8_SB(0, 0), cB, voffB); PG8_STAGE(PG8_SB(0, 1), cB + hstepB, voffB); PG8_STAGE(PG8_SA(0, 0), cA, voffA); PG8_STAGE(PG8_SA(0, 1), cA + hstepA, voffA);
;   if (wr == 1) PG8_BAR;
;   PG8_WAIT_V(2); PG8_BAR;
;   PG8_STAGE(PG8_SB(1, 0), cB + kstep, voffB); PG8_STAGE(PG8_SA(1, 0), cA + kstep, voffA); PG8_STAGE(PG8_SB(1, 1), cB + hstepB + kstep, voffB);
;   PG8_WAIT_V(6); PG8_BAR;
;   for (;;) {
;     const bool has_next = S.next(ui + 1, nxt);
;     const char* nA = has_next ? PG8_UA(nxt) : cA; const char* nB = has_next ? PG8_UB(nxt) : cB;
;     for (int t = 0; t < nt; t += 2) {
;       const bool last = (t == nt - 2);
;       const char* a1 = cA + (size_t)(t + 1) * kstep;
;       const char* a2 = last ? nA : cA + (size_t)(t + 2) * kstep; const char* b2 = last ? nB : cB + (size_t)(t + 2) * kstep;
;       const char* a3 = a2 + kstep; const char* b3 = b2 + kstep;
.LBB0_327:
	v_mov_b32_e32 v129, 0
	s_andn2_b64 vcc, exec, s[20:21]
	v_mov_b32_e32 v128, v129
	v_mov_b32_e32 v127, v129
	v_mov_b32_e32 v126, v129
	v_mov_b32_e32 v125, v129
	v_mov_b32_e32 v124, v129
	v_mov_b32_e32 v123, v129
	v_mov_b32_e32 v122, v129
	v_mov_b32_e32 v113, v129
	v_mov_b32_e32 v112, v129
	v_mov_b32_e32 v111, v129
	v_mov_b32_e32 v110, v129
	v_mov_b32_e32 v109, v129
	v_mov_b32_e32 v108, v129
	v_mov_b32_e32 v107, v129
	v_mov_b32_e32 v106, v129
	v_mov_b32_e32 v97, v129
	v_mov_b32_e32 v96, v129
	v_mov_b32_e32 v95, v129
	v_mov_b32_e32 v94, v129
	v_mov_b32_e32 v93, v129
	v_mov_b32_e32 v92, v129
	v_mov_b32_e32 v91, v129
	v_mov_b32_e32 v90, v129
	v_mov_b32_e32 v81, v129
	v_mov_b32_e32 v80, v129
	v_mov_b32_e32 v79, v129
	v_mov_b32_e32 v78, v129
	v_mov_b32_e32 v77, v129
	v_mov_b32_e32 v76, v129
	v_mov_b32_e32 v75, v129
	v_mov_b32_e32 v74, v129
	v_mov_b32_e32 v121, v129
	v_mov_b32_e32 v120, v129
	v_mov_b32_e32 v119, v129
	v_mov_b32_e32 v118, v129
	v_mov_b32_e32 v117, v129
	v_mov_b32_e32 v116, v129
	v_mov_b32_e32 v115, v129
	v_mov_b32_e32 v114, v129
	v_mov_b32_e32 v105, v129
	v_mov_b32_e32 v104, v129
	v_mov_b32_e32 v103, v129
	v_mov_b32_e32 v102, v129
	v_mov_b32_e32 v101, v129
	v_mov_b32_e32 v100, v129
	v_mov_b32_e32 v99, v129
	v_mov_b32_e32 v98, v129
	v_mov_b32_e32 v89, v129
	v_mov_b32_e32 v88, v129
	v_mov_b32_e32 v87, v129
	v_mov_b32_e32 v86, v129
	v_mov_b32_e32 v85, v129
	v_mov_b32_e32 v84, v129
	v_mov_b32_e32 v83, v129
	v_mov_b32_e32 v82, v129
	v_mov_b32_e32 v73, v129
	v_mov_b32_e32 v72, v129
	v_mov_b32_e32 v71, v129
	v_mov_b32_e32 v70, v129
	v_mov_b32_e32 v69, v129
	v_mov_b32_e32 v68, v129
	v_mov_b32_e32 v67, v129
	v_mov_b32_e32 v66, v129
	v_mov_b32_e32 v65, v129
	v_mov_b32_e32 v64, v129
	v_mov_b32_e32 v63, v129
	v_mov_b32_e32 v62, v129
	v_mov_b32_e32 v61, v129
	v_mov_b32_e32 v60, v129
	v_mov_b32_e32 v59, v129
	v_mov_b32_e32 v58, v129
	v_mov_b32_e32 v49, v129
	v_mov_b32_e32 v48, v129
	v_mov_b32_e32 v47, v129
	v_mov_b32_e32 v46, v129
	v_mov_b32_e32 v45, v129
	v_mov_b32_e32 v44, v129
	v_mov_b32_e32 v43, v129
	v_mov_b32_e32 v42, v129
	v_mov_b32_e32 v33, v129
	v_mov_b32_e32 v32, v129
	v_mov_b32_e32 v31, v129
	v_mov_b32_e32 v30, v129
	v_mov_b32_e32 v29, v129
	v_mov_b32_e32 v28, v129
	v_mov_b32_e32 v27, v129
	v_mov_b32_e32 v26, v129
	v_mov_b32_e32 v17, v129
	v_mov_b32_e32 v16, v129
	v_mov_b32_e32 v15, v129
	v_mov_b32_e32 v14, v129
	v_mov_b32_e32 v13, v129
	v_mov_b32_e32 v12, v129
	v_mov_b32_e32 v11, v129
	v_mov_b32_e32 v10, v129
	v_mov_b32_e32 v57, v129
	v_mov_b32_e32 v56, v129
	v_mov_b32_e32 v55, v129
	v_mov_b32_e32 v54, v129
	v_mov_b32_e32 v53, v129
	v_mov_b32_e32 v52, v129
	v_mov_b32_e32 v51, v129
	v_mov_b32_e32 v50, v129
	v_mov_b32_e32 v41, v129
	v_mov_b32_e32 v40, v129
	v_mov_b32_e32 v39, v129
	v_mov_b32_e32 v38, v129
	v_mov_b32_e32 v37, v129
	v_mov_b32_e32 v36, v129
	v_mov_b32_e32 v35, v129
	v_mov_b32_e32 v34, v129
	v_mov_b32_e32 v25, v129
	v_mov_b32_e32 v24, v129
	v_mov_b32_e32 v23, v129
	v_mov_b32_e32 v22, v129
	v_mov_b32_e32 v21, v129
	v_mov_b32_e32 v20, v129
	v_mov_b32_e32 v19, v129
	v_mov_b32_e32 v18, v129
	v_mov_b32_e32 v9, v129
	v_mov_b32_e32 v8, v129
	v_mov_b32_e32 v7, v129
	v_mov_b32_e32 v6, v129
	v_mov_b32_e32 v5, v129
	v_mov_b32_e32 v4, v129
	v_mov_b32_e32 v3, v129
	v_mov_b32_e32 v2, v129
	s_cbranch_vccnz .LBB0_330
	s_add_u32 s44, s48, 0x80
	s_addc_u32 s45, s49, 0
	s_add_u32 s48, s46, 0x100
	v_mov_b32_e32 v2, 0
	s_addc_u32 s49, s47, 0
	s_mov_b32 s46, 0
	v_mov_b32_e32 v3, v2
	v_mov_b32_e32 v4, v2
	v_mov_b32_e32 v5, v2
	v_mov_b32_e32 v6, v2
	v_mov_b32_e32 v7, v2
	v_mov_b32_e32 v8, v2
	v_mov_b32_e32 v9, v2
	v_mov_b32_e32 v18, v2
	v_mov_b32_e32 v19, v2
	v_mov_b32_e32 v20, v2
	v_mov_b32_e32 v21, v2
	v_mov_b32_e32 v22, v2
	v_mov_b32_e32 v23, v2
	v_mov_b32_e32 v24, v2
	v_mov_b32_e32 v25, v2
	v_mov_b32_e32 v34, v2
	v_mov_b32_e32 v35, v2
	v_mov_b32_e32 v36, v2
	v_mov_b32_e32 v37, v2
	v_mov_b32_e32 v38, v2
	v_mov_b32_e32 v39, v2
	v_mov_b32_e32 v40, v2
	v_mov_b32_e32 v41, v2
	v_mov_b32_e32 v50, v2
	v_mov_b32_e32 v51, v2
	v_mov_b32_e32 v52, v2
	v_mov_b32_e32 v53, v2
	v_mov_b32_e32 v54, v2
	v_mov_b32_e32 v55, v2
	v_mov_b32_e32 v56, v2
	v_mov_b32_e32 v57, v2
	v_mov_b32_e32 v10, v2
	v_mov_b32_e32 v11, v2
	v_mov_b32_e32 v12, v2
	v_mov_b32_e32 v13, v2
	v_mov_b32_e32 v14, v2
	v_mov_b32_e32 v15, v2
	v_mov_b32_e32 v16, v2
	v_mov_b32_e32 v17, v2
	v_mov_b32_e32 v26, v2
	v_mov_b32_e32 v27, v2
	v_mov_b32_e32 v28, v2
	v_mov_b32_e32 v29, v2
	v_mov_b32_e32 v30, v2
	v_mov_b32_e32 v31, v2
	v_mov_b32_e32 v32, v2
	v_mov_b32_e32 v33, v2
	v_mov_b32_e32 v42, v2
	v_mov_b32_e32 v43, v2
	v_mov_b32_e32 v44, v2
	v_mov_b32_e32 v45, v2
	v_mov_b32_e32 v46, v2
	v_mov_b32_e32 v47, v2
	v_mov_b32_e32 v48, v2
	v_mov_b32_e32 v49, v2
	v_mov_b32_e32 v58, v2
	v_mov_b32_e32 v59, v2
	v_mov_b32_e32 v60, v2
	v_mov_b32_e32 v61, v2
	v_mov_b32_e32 v62, v2
	v_mov_b32_e32 v63, v2
	v_mov_b32_e32 v64, v2
	v_mov_b32_e32 v65, v2
	v_mov_b32_e32 v66, v2
	v_mov_b32_e32 v67, v2
	v_mov_b32_e32 v68, v2
	v_mov_b32_e32 v69, v2
	v_mov_b32_e32 v70, v2
	v_mov_b32_e32 v71, v2
	v_mov_b32_e32 v72, v2
	v_mov_b32_e32 v73, v2
	v_mov_b32_e32 v82, v2
	v_mov_b32_e32 v83, v2
	v_mov_b32_e32 v84, v2
	v_mov_b32_e32 v85, v2
	v_mov_b32_e32 v86, v2
	v_mov_b32_e32 v87, v2
	v_mov_b32_e32 v88, v2
	v_mov_b32_e32 v89, v2
	v_mov_b32_e32 v98, v2
	v_mov_b32_e32 v99, v2
	v_mov_b32_e32 v100, v2
	v_mov_b32_e32 v101, v2
	v_mov_b32_e32 v102, v2
	v_mov_b32_e32 v103, v2
	v_mov_b32_e32 v104, v2
	v_mov_b32_e32 v105, v2
	v_mov_b32_e32 v114, v2
	v_mov_b32_e32 v115, v2
	v_mov_b32_e32 v116, v2
	v_mov_b32_e32 v117, v2
	v_mov_b32_e32 v118, v2
	v_mov_b32_e32 v119, v2
	v_mov_b32_e32 v120, v2
	v_mov_b32_e32 v121, v2
	v_mov_b32_e32 v74, v2
	v_mov_b32_e32 v75, v2
	v_mov_b32_e32 v76, v2
	v_mov_b32_e32 v77, v2
	v_mov_b32_e32 v78, v2
	v_mov_b32_e32 v79, v2
	v_mov_b32_e32 v80, v2
	v_mov_b32_e32 v81, v2
	v_mov_b32_e32 v90, v2
	v_mov_b32_e32 v91, v2
	v_mov_b32_e32 v92, v2
	v_mov_b32_e32 v93, v2
	v_mov_b32_e32 v94, v2
	v_mov_b32_e32 v95, v2
	v_mov_b32_e32 v96, v2
	v_mov_b32_e32 v97, v2
	v_mov_b32_e32 v106, v2
	v_mov_b32_e32 v107, v2
	v_mov_b32_e32 v108, v2
	v_mov_b32_e32 v109, v2
	v_mov_b32_e32 v110, v2
	v_mov_b32_e32 v111, v2
	v_mov_b32_e32 v112, v2
	v_mov_b32_e32 v113, v2
	v_mov_b32_e32 v122, v2
	v_mov_b32_e32 v123, v2
	v_mov_b32_e32 v124, v2
	v_mov_b32_e32 v125, v2
	v_mov_b32_e32 v126, v2
	v_mov_b32_e32 v127, v2
	v_mov_b32_e32 v128, v2
	v_mov_b32_e32 v129, v2
	.p2align	7

; #define PG8_STAGE(bufoff, gbase, voff) do { _Pragma("unroll") for (int _i = 0; _i < 2; ++_i) \
;     __builtin_amdgcn_global_load_lds((const unsigned*)((const char*)(gbase) + (voff)[_i]), (LAS unsigned*)(lds + (bufoff) + ldsw + _i * 8192), 16, 0, 0); } while (0)
; #define PG8_WAIT_V(n) asm volatile("s_waitcnt vmcnt(" #n ")" ::: "memory")
; #define PG8_BAR __builtin_amdgcn_s_barrier()
; template <class Epi>
; DI void gemm_phase(LAS unsigned char* lds, const Gemm g, const StaticOrder& S, const Epi& E) {
;     ...
;   Unit cur, nxt; int ui = 0;
;   if (!S.next(0, cur)) return;
;   f32x4 acc[2][2][4][2];
; #pragma unroll
;   for (int a = 0; a < 2; ++a)
; #pragma unroll
;     for (int b = 0; b < 2; ++b)
; #pragma unroll
;       for (int m = 0; m < 4; ++m)
; #pragma unroll
;         for (int n = 0; n < 2; ++n) acc[a][b][m][n] = (f32x4){0.f, 0.f, 0.f, 0.f};
;   bf16x8 At[4][2], B0[2][2], B1[2][2];
;   const char* cA = PG8_UA(cur); const char* cB = PG8_UB(cur);
;   PG8_STAGE(PG8_SB(0, 0), cB, voffB); PG8_STAGE(PG8_SB(0, 1), cB + hstepB, voffB); PG8_STAGE(PG8_SA(0, 0), cA, voffA); PG8_STAGE(PG8_SA(0, 1), cA + hstepA, voffA);
;   if (wr == 1) PG8_BAR;
;   PG8_WAIT_V(2); PG8_BAR;
;   PG8_STAGE(PG8_SB(1, 0), cB + kstep, voffB); PG8_STAGE(PG8_SA(1, 0), cA + kstep, voffA); PG8_STAGE(PG8_SB(1, 1), cB + hstepB + kstep, voffB);
;   PG8_WAIT_V(6); PG8_BAR;
;   for (;;) {
;     const bool has_next = S.next(ui + 1, nxt);
;     const char* nA = has_next ? PG8_UA(nxt) : cA; const char* nB = has_next ? PG8_UB(nxt) : cB;
;     for (int t = 0; t < nt; t += 2) {
;       const bool last = (t == nt - 2);
;       const char* a1 = cA + (size_t)(t + 1) * kstep;
;       const char* a2 = last ? nA : cA + (size_t)(t + 2) * kstep; const char* b2 = last ? nB : cB + (size_t)(t + 2) * kstep;
;       const char* a3 = a2 + kstep; const char* b3 = b2 + kstep;
.LBB0_553:
	v_mov_b32_e32 v153, 0
	s_andn2_b64 vcc, exec, s[14:15]
	v_mov_b32_e32 v152, v153
	v_mov_b32_e32 v151, v153
	v_mov_b32_e32 v150, v153
	v_mov_b32_e32 v149, v153
	v_mov_b32_e32 v148, v153
	v_mov_b32_e32 v147, v153
	v_mov_b32_e32 v146, v153
	v_mov_b32_e32 v137, v153
	v_mov_b32_e32 v136, v153
	v_mov_b32_e32 v135, v153
	v_mov_b32_e32 v134, v153
	v_mov_b32_e32 v133, v153
	v_mov_b32_e32 v132, v153
	v_mov_b32_e32 v131, v153
	v_mov_b32_e32 v130, v153
	v_mov_b32_e32 v121, v153
	v_mov_b32_e32 v120, v153
	v_mov_b32_e32 v119, v153
	v_mov_b32_e32 v118, v153
	v_mov_b32_e32 v117, v153
	v_mov_b32_e32 v116, v153
	v_mov_b32_e32 v115, v153
	v_mov_b32_e32 v114, v153
	v_mov_b32_e32 v105, v153
	v_mov_b32_e32 v104, v153
	v_mov_b32_e32 v103, v153
	v_mov_b32_e32 v102, v153
	v_mov_b32_e32 v101, v153
	v_mov_b32_e32 v100, v153
	v_mov_b32_e32 v99, v153
	v_mov_b32_e32 v98, v153
	v_mov_b32_e32 v141, v153
	v_mov_b32_e32 v140, v153
	v_mov_b32_e32 v139, v153
	v_mov_b32_e32 v138, v153
	v_mov_b32_e32 v145, v153
	v_mov_b32_e32 v144, v153
	v_mov_b32_e32 v143, v153
	v_mov_b32_e32 v142, v153
	v_mov_b32_e32 v125, v153
	v_mov_b32_e32 v124, v153
	v_mov_b32_e32 v123, v153
	v_mov_b32_e32 v122, v153
	v_mov_b32_e32 v129, v153
	v_mov_b32_e32 v128, v153
	v_mov_b32_e32 v127, v153
	v_mov_b32_e32 v126, v153
	v_mov_b32_e32 v109, v153
	v_mov_b32_e32 v108, v153
	v_mov_b32_e32 v107, v153
	v_mov_b32_e32 v106, v153
	v_mov_b32_e32 v113, v153
	v_mov_b32_e32 v112, v153
	v_mov_b32_e32 v111, v153
	v_mov_b32_e32 v110, v153
	v_mov_b32_e32 v93, v153
	v_mov_b32_e32 v92, v153
	v_mov_b32_e32 v91, v153
	v_mov_b32_e32 v90, v153
	v_mov_b32_e32 v97, v153
	v_mov_b32_e32 v96, v153
	v_mov_b32_e32 v95, v153
	v_mov_b32_e32 v94, v153
	v_mov_b32_e32 v89, v153
	v_mov_b32_e32 v88, v153
	v_mov_b32_e32 v87, v153
	v_mov_b32_e32 v86, v153
	v_mov_b32_e32 v85, v153
	v_mov_b32_e32 v84, v153
	v_mov_b32_e32 v83, v153
	v_mov_b32_e32 v82, v153
	v_mov_b32_e32 v73, v153
	v_mov_b32_e32 v72, v153
	v_mov_b32_e32 v71, v153
	v_mov_b32_e32 v70, v153
	v_mov_b32_e32 v61, v153
	v_mov_b32_e32 v60, v153
	v_mov_b32_e32 v59, v153
	v_mov_b32_e32 v58, v153
	v_mov_b32_e32 v33, v153
	v_mov_b32_e32 v32, v153
	v_mov_b32_e32 v31, v153
	v_mov_b32_e32 v30, v153
	v_mov_b32_e32 v29, v153
	v_mov_b32_e32 v28, v153
	v_mov_b32_e32 v27, v153
	v_mov_b32_e32 v26, v153
	v_mov_b32_e32 v17, v153
	v_mov_b32_e32 v16, v153
	v_mov_b32_e32 v15, v153
	v_mov_b32_e32 v14, v153
	v_mov_b32_e32 v13, v153
	v_mov_b32_e32 v12, v153
	v_mov_b32_e32 v11, v153
	v_mov_b32_e32 v10, v153
	v_mov_b32_e32 v77, v153
	v_mov_b32_e32 v76, v153
	v_mov_b32_e32 v75, v153
	v_mov_b32_e32 v74, v153
	v_mov_b32_e32 v81, v153
	v_mov_b32_e32 v80, v153
	v_mov_b32_e32 v79, v153
	v_mov_b32_e32 v78, v153
	v_mov_b32_e32 v41, v153
	v_mov_b32_e32 v40, v153
	v_mov_b32_e32 v39, v153
	v_mov_b32_e32 v38, v153
	v_mov_b32_e32 v49, v153
	v_mov_b32_e32 v48, v153
	v_mov_b32_e32 v47, v153
	v_mov_b32_e32 v46, v153
	v_mov_b32_e32 v21, v153
	v_mov_b32_e32 v20, v153
	v_mov_b32_e32 v19, v153
	v_mov_b32_e32 v18, v153
	v_mov_b32_e32 v25, v153
	v_mov_b32_e32 v24, v153
	v_mov_b32_e32 v23, v153
	v_mov_b32_e32 v22, v153
	v_mov_b32_e32 v5, v153
	v_mov_b32_e32 v4, v153
	v_mov_b32_e32 v3, v153
	v_mov_b32_e32 v2, v153
	v_mov_b32_e32 v9, v153
	v_mov_b32_e32 v8, v153
	v_mov_b32_e32 v7, v153
	v_mov_b32_e32 v6, v153
	s_cbranch_vccnz .LBB0_557
	s_add_u32 s42, s62, 0x80
	s_addc_u32 s43, s63, 0
	s_add_u32 s62, s54, 0x100
	v_mov_b32_e32 v6, 0
	s_addc_u32 s63, s55, 0
	s_mov_b32 s54, 0
	v_mov_b32_e32 v7, v6
	v_mov_b32_e32 v8, v6
	v_mov_b32_e32 v9, v6
	v_mov_b32_e32 v2, v6
	v_mov_b32_e32 v3, v6
	v_mov_b32_e32 v4, v6
	v_mov_b32_e32 v5, v6
	v_mov_b32_e32 v22, v6
	v_mov_b32_e32 v23, v6
	v_mov_b32_e32 v24, v6
	v_mov_b32_e32 v25, v6
	v_mov_b32_e32 v18, v6
	v_mov_b32_e32 v19, v6
	v_mov_b32_e32 v20, v6
	v_mov_b32_e32 v21, v6
	v_mov_b32_e32 v46, v6
	v_mov_b32_e32 v47, v6
	v_mov_b32_e32 v48, v6
	v_mov_b32_e32 v49, v6
	v_mov_b32_e32 v38, v6
	v_mov_b32_e32 v39, v6
	v_mov_b32_e32 v40, v6
	v_mov_b32_e32 v41, v6
	v_mov_b32_e32 v78, v6
	v_mov_b32_e32 v79, v6
	v_mov_b32_e32 v80, v6
	v_mov_b32_e32 v81, v6
	v_mov_b32_e32 v74, v6
	v_mov_b32_e32 v75, v6
	v_mov_b32_e32 v76, v6
	v_mov_b32_e32 v77, v6
	v_mov_b32_e32 v10, v6
	v_mov_b32_e32 v11, v6
	v_mov_b32_e32 v12, v6
	v_mov_b32_e32 v13, v6
	v_mov_b32_e32 v14, v6
	v_mov_b32_e32 v15, v6
	v_mov_b32_e32 v16, v6
	v_mov_b32_e32 v17, v6
	v_mov_b32_e32 v26, v6
	v_mov_b32_e32 v27, v6
	v_mov_b32_e32 v28, v6
	v_mov_b32_e32 v29, v6
	v_mov_b32_e32 v30, v6
	v_mov_b32_e32 v31, v6
	v_mov_b32_e32 v32, v6
	v_mov_b32_e32 v33, v6
	v_mov_b32_e32 v58, v6
	v_mov_b32_e32 v59, v6
	v_mov_b32_e32 v60, v6
	v_mov_b32_e32 v61, v6
	v_mov_b32_e32 v70, v6
	v_mov_b32_e32 v71, v6
	v_mov_b32_e32 v72, v6
	v_mov_b32_e32 v73, v6
	v_mov_b32_e32 v82, v6
	v_mov_b32_e32 v83, v6
	v_mov_b32_e32 v84, v6
	v_mov_b32_e32 v85, v6
	v_mov_b32_e32 v86, v6
	v_mov_b32_e32 v87, v6
	v_mov_b32_e32 v88, v6
	v_mov_b32_e32 v89, v6
	v_mov_b32_e32 v94, v6
	v_mov_b32_e32 v95, v6
	v_mov_b32_e32 v96, v6
	v_mov_b32_e32 v97, v6
	v_mov_b32_e32 v90, v6
	v_mov_b32_e32 v91, v6
	v_mov_b32_e32 v92, v6
	v_mov_b32_e32 v93, v6
	v_mov_b32_e32 v110, v6
	v_mov_b32_e32 v111, v6
	v_mov_b32_e32 v112, v6
	v_mov_b32_e32 v113, v6
	v_mov_b32_e32 v106, v6
	v_mov_b32_e32 v107, v6
	v_mov_b32_e32 v108, v6
	v_mov_b32_e32 v109, v6
	v_mov_b32_e32 v126, v6
	v_mov_b32_e32 v127, v6
	v_mov_b32_e32 v128, v6
	v_mov_b32_e32 v129, v6
	v_mov_b32_e32 v122, v6
	v_mov_b32_e32 v123, v6
	v_mov_b32_e32 v124, v6
	v_mov_b32_e32 v125, v6
	v_mov_b32_e32 v142, v6
	v_mov_b32_e32 v143, v6
	v_mov_b32_e32 v144, v6
	v_mov_b32_e32 v145, v6
	v_mov_b32_e32 v138, v6
	v_mov_b32_e32 v139, v6
	v_mov_b32_e32 v140, v6
	v_mov_b32_e32 v141, v6
	v_mov_b32_e32 v98, v6
	v_mov_b32_e32 v99, v6
	v_mov_b32_e32 v100, v6
	v_mov_b32_e32 v101, v6
	v_mov_b32_e32 v102, v6
	v_mov_b32_e32 v103, v6
	v_mov_b32_e32 v104, v6
	v_mov_b32_e32 v105, v6
	v_mov_b32_e32 v114, v6
	v_mov_b32_e32 v115, v6
	v_mov_b32_e32 v116, v6
	v_mov_b32_e32 v117, v6
	v_mov_b32_e32 v118, v6
	v_mov_b32_e32 v119, v6
	v_mov_b32_e32 v120, v6
	v_mov_b32_e32 v121, v6
	v_mov_b32_e32 v130, v6
	v_mov_b32_e32 v131, v6
	v_mov_b32_e32 v132, v6
	v_mov_b32_e32 v133, v6
	v_mov_b32_e32 v134, v6
	v_mov_b32_e32 v135, v6
	v_mov_b32_e32 v136, v6
	v_mov_b32_e32 v137, v6
	v_mov_b32_e32 v146, v6
	v_mov_b32_e32 v147, v6
	v_mov_b32_e32 v148, v6
	v_mov_b32_e32 v149, v6
	v_mov_b32_e32 v150, v6
	v_mov_b32_e32 v151, v6
	v_mov_b32_e32 v152, v6
	v_mov_b32_e32 v153, v6
	.p2align	7

; #define PG8_STAGE(bufoff, gbase, voff) do { _Pragma("unroll") for (int _i = 0; _i < 2; ++_i) \
;     __builtin_amdgcn_global_load_lds((const unsigned*)((const char*)(gbase) + (voff)[_i]), (LAS unsigned*)(lds + (bufoff) + ldsw + _i * 8192), 16, 0, 0); } while (0)
; #define PG8_WAIT_V(n) asm volatile("s_waitcnt vmcnt(" #n ")" ::: "memory")
; #define PG8_BAR __builtin_amdgcn_s_barrier()
; template <class Epi>
; DI void gemm_phase(LAS unsigned char* lds, const Gemm g, const StaticOrder& S, const Epi& E) {
;     ...
;   Unit cur, nxt; int ui = 0;
;   if (!S.next(0, cur)) return;
;   f32x4 acc[2][2][4][2];
; #pragma unroll
;   for (int a = 0; a < 2; ++a)
; #pragma unroll
;     for (int b = 0; b < 2; ++b)
; #pragma unroll
;       for (int m = 0; m < 4; ++m)
; #pragma unroll
;         for (int n = 0; n < 2; ++n) acc[a][b][m][n] = (f32x4){0.f, 0.f, 0.f, 0.f};
;   bf16x8 At[4][2], B0[2][2], B1[2][2];
;   const char* cA = PG8_UA(cur); const char* cB = PG8_UB(cur);
;   PG8_STAGE(PG8_SB(0, 0), cB, voffB); PG8_STAGE(PG8_SB(0, 1), cB + hstepB, voffB); PG8_STAGE(PG8_SA(0, 0), cA, voffA); PG8_STAGE(PG8_SA(0, 1), cA + hstepA, voffA);
;   if (wr == 1) PG8_BAR;
;   PG8_WAIT_V(2); PG8_BAR;
;   PG8_STAGE(PG8_SB(1, 0), cB + kstep, voffB); PG8_STAGE(PG8_SA(1, 0), cA + kstep, voffA); PG8_STAGE(PG8_SB(1, 1), cB + hstepB + kstep, voffB);
;   PG8_WAIT_V(6); PG8_BAR;
;   for (;;) {
;     const bool has_next = S.next(ui + 1, nxt);
;     const char* nA = has_next ? PG8_UA(nxt) : cA; const char* nB = has_next ? PG8_UB(nxt) : cB;
;     for (int t = 0; t < nt; t += 2) {
;       const bool last = (t == nt - 2);
;       const char* a1 = cA + (size_t)(t + 1) * kstep;
;       const char* a2 = last ? nA : cA + (size_t)(t + 2) * kstep; const char* b2 = last ? nB : cB + (size_t)(t + 2) * kstep;
;       const char* a3 = a2 + kstep; const char* b3 = b2 + kstep;
.LBB0_842:
	v_readlane_b32 s44, v250, 48
	v_mov_b32_e32 v129, 0
	v_readlane_b32 s45, v250, 49
	s_andn2_b64 vcc, exec, s[44:45]
	v_mov_b32_e32 v128, v129
	v_mov_b32_e32 v127, v129
	v_mov_b32_e32 v126, v129
	v_mov_b32_e32 v125, v129
	v_mov_b32_e32 v124, v129
	v_mov_b32_e32 v123, v129
	v_mov_b32_e32 v122, v129
	v_mov_b32_e32 v113, v129
	v_mov_b32_e32 v112, v129
	v_mov_b32_e32 v111, v129
	v_mov_b32_e32 v110, v129
	v_mov_b32_e32 v109, v129
	v_mov_b32_e32 v108, v129
	v_mov_b32_e32 v107, v129
	v_mov_b32_e32 v106, v129
	v_mov_b32_e32 v97, v129
	v_mov_b32_e32 v96, v129
	v_mov_b32_e32 v95, v129
	v_mov_b32_e32 v94, v129
	v_mov_b32_e32 v93, v129
	v_mov_b32_e32 v92, v129
	v_mov_b32_e32 v91, v129
	v_mov_b32_e32 v90, v129
	v_mov_b32_e32 v81, v129
	v_mov_b32_e32 v80, v129
	v_mov_b32_e32 v79, v129
	v_mov_b32_e32 v78, v129
	v_mov_b32_e32 v77, v129
	v_mov_b32_e32 v76, v129
	v_mov_b32_e32 v75, v129
	v_mov_b32_e32 v74, v129
	v_mov_b32_e32 v121, v129
	v_mov_b32_e32 v120, v129
	v_mov_b32_e32 v119, v129
	v_mov_b32_e32 v118, v129
	v_mov_b32_e32 v117, v129
	v_mov_b32_e32 v116, v129
	v_mov_b32_e32 v115, v129
	v_mov_b32_e32 v114, v129
	v_mov_b32_e32 v105, v129
	v_mov_b32_e32 v104, v129
	v_mov_b32_e32 v103, v129
	v_mov_b32_e32 v102, v129
	v_mov_b32_e32 v101, v129
	v_mov_b32_e32 v100, v129
	v_mov_b32_e32 v99, v129
	v_mov_b32_e32 v98, v129
	v_mov_b32_e32 v89, v129
	v_mov_b32_e32 v88, v129
	v_mov_b32_e32 v87, v129
	v_mov_b32_e32 v86, v129
	v_mov_b32_e32 v85, v129
	v_mov_b32_e32 v84, v129
	v_mov_b32_e32 v83, v129
	v_mov_b32_e32 v82, v129
	v_mov_b32_e32 v73, v129
	v_mov_b32_e32 v72, v129
	v_mov_b32_e32 v71, v129
	v_mov_b32_e32 v70, v129
	v_mov_b32_e32 v69, v129
	v_mov_b32_e32 v68, v129
	v_mov_b32_e32 v67, v129
	v_mov_b32_e32 v66, v129
	v_mov_b32_e32 v65, v129
	v_mov_b32_e32 v64, v129
	v_mov_b32_e32 v63, v129
	v_mov_b32_e32 v62, v129
	v_mov_b32_e32 v61, v129
	v_mov_b32_e32 v60, v129
	v_mov_b32_e32 v59, v129
	v_mov_b32_e32 v58, v129
	v_mov_b32_e32 v49, v129
	v_mov_b32_e32 v48, v129
	v_mov_b32_e32 v47, v129
	v_mov_b32_e32 v46, v129
	v_mov_b32_e32 v45, v129
	v_mov_b32_e32 v44, v129
	v_mov_b32_e32 v43, v129
	v_mov_b32_e32 v42, v129
	v_mov_b32_e32 v33, v129
	v_mov_b32_e32 v32, v129
	v_mov_b32_e32 v31, v129
	v_mov_b32_e32 v30, v129
	v_mov_b32_e32 v29, v129
	v_mov_b32_e32 v28, v129
	v_mov_b32_e32 v27, v129
	v_mov_b32_e32 v26, v129
	v_mov_b32_e32 v17, v129
	v_mov_b32_e32 v16, v129
	v_mov_b32_e32 v15, v129
	v_mov_b32_e32 v14, v129
	v_mov_b32_e32 v13, v129
	v_mov_b32_e32 v12, v129
	v_mov_b32_e32 v11, v129
	v_mov_b32_e32 v10, v129
	v_mov_b32_e32 v57, v129
	v_mov_b32_e32 v56, v129
	v_mov_b32_e32 v55, v129
	v_mov_b32_e32 v54, v129
	v_mov_b32_e32 v53, v129
	v_mov_b32_e32 v52, v129
	v_mov_b32_e32 v51, v129
	v_mov_b32_e32 v50, v129
	v_mov_b32_e32 v41, v129
	v_mov_b32_e32 v40, v129
	v_mov_b32_e32 v39, v129
	v_mov_b32_e32 v38, v129
	v_mov_b32_e32 v37, v129
	v_mov_b32_e32 v36, v129
	v_mov_b32_e32 v35, v129
	v_mov_b32_e32 v34, v129
	v_mov_b32_e32 v25, v129
	v_mov_b32_e32 v24, v129
	v_mov_b32_e32 v23, v129
	v_mov_b32_e32 v22, v129
	v_mov_b32_e32 v21, v129
	v_mov_b32_e32 v20, v129
	v_mov_b32_e32 v19, v129
	v_mov_b32_e32 v18, v129
	v_mov_b32_e32 v9, v129
	v_mov_b32_e32 v8, v129
	v_mov_b32_e32 v7, v129
	v_mov_b32_e32 v6, v129
	v_mov_b32_e32 v5, v129
	v_mov_b32_e32 v4, v129
	v_mov_b32_e32 v3, v129
	v_mov_b32_e32 v2, v129
	s_cbranch_vccnz .LBB0_845
	s_add_u32 s44, s48, 0x80
	s_addc_u32 s45, s49, 0
	s_add_u32 s23, s46, 0x100
	v_mov_b32_e32 v2, 0
	s_addc_u32 s48, s47, 0
	s_mov_b32 s46, 0
	v_mov_b32_e32 v3, v2
	v_mov_b32_e32 v4, v2
	v_mov_b32_e32 v5, v2
	v_mov_b32_e32 v6, v2
	v_mov_b32_e32 v7, v2
	v_mov_b32_e32 v8, v2
	v_mov_b32_e32 v9, v2
	v_mov_b32_e32 v18, v2
	v_mov_b32_e32 v19, v2
	v_mov_b32_e32 v20, v2
	v_mov_b32_e32 v21, v2
	v_mov_b32_e32 v22, v2
	v_mov_b32_e32 v23, v2
	v_mov_b32_e32 v24, v2
	v_mov_b32_e32 v25, v2
	v_mov_b32_e32 v34, v2
	v_mov_b32_e32 v35, v2
	v_mov_b32_e32 v36, v2
	v_mov_b32_e32 v37, v2
	v_mov_b32_e32 v38, v2
	v_mov_b32_e32 v39, v2
	v_mov_b32_e32 v40, v2
	v_mov_b32_e32 v41, v2
	v_mov_b32_e32 v50, v2
	v_mov_b32_e32 v51, v2
	v_mov_b32_e32 v52, v2
	v_mov_b32_e32 v53, v2
	v_mov_b32_e32 v54, v2
	v_mov_b32_e32 v55, v2
	v_mov_b32_e32 v56, v2
	v_mov_b32_e32 v57, v2
	v_mov_b32_e32 v10, v2
	v_mov_b32_e32 v11, v2
	v_mov_b32_e32 v12, v2
	v_mov_b32_e32 v13, v2
	v_mov_b32_e32 v14, v2
	v_mov_b32_e32 v15, v2
	v_mov_b32_e32 v16, v2
	v_mov_b32_e32 v17, v2
	v_mov_b32_e32 v26, v2
	v_mov_b32_e32 v27, v2
	v_mov_b32_e32 v28, v2
	v_mov_b32_e32 v29, v2
	v_mov_b32_e32 v30, v2
	v_mov_b32_e32 v31, v2
	v_mov_b32_e32 v32, v2
	v_mov_b32_e32 v33, v2
	v_mov_b32_e32 v42, v2
	v_mov_b32_e32 v43, v2
	v_mov_b32_e32 v44, v2
	v_mov_b32_e32 v45, v2
	v_mov_b32_e32 v46, v2
	v_mov_b32_e32 v47, v2
	v_mov_b32_e32 v48, v2
	v_mov_b32_e32 v49, v2
	v_mov_b32_e32 v58, v2
	v_mov_b32_e32 v59, v2
	v_mov_b32_e32 v60, v2
	v_mov_b32_e32 v61, v2
	v_mov_b32_e32 v62, v2
	v_mov_b32_e32 v63, v2
	v_mov_b32_e32 v64, v2
	v_mov_b32_e32 v65, v2
	v_mov_b32_e32 v66, v2
	v_mov_b32_e32 v67, v2
	v_mov_b32_e32 v68, v2
	v_mov_b32_e32 v69, v2
	v_mov_b32_e32 v70, v2
	v_mov_b32_e32 v71, v2
	v_mov_b32_e32 v72, v2
	v_mov_b32_e32 v73, v2
	v_mov_b32_e32 v82, v2
	v_mov_b32_e32 v83, v2
	v_mov_b32_e32 v84, v2
	v_mov_b32_e32 v85, v2
	v_mov_b32_e32 v86, v2
	v_mov_b32_e32 v87, v2
	v_mov_b32_e32 v88, v2
	v_mov_b32_e32 v89, v2
	v_mov_b32_e32 v98, v2
	v_mov_b32_e32 v99, v2
	v_mov_b32_e32 v100, v2
	v_mov_b32_e32 v101, v2
	v_mov_b32_e32 v102, v2
	v_mov_b32_e32 v103, v2
	v_mov_b32_e32 v104, v2
	v_mov_b32_e32 v105, v2
	v_mov_b32_e32 v114, v2
	v_mov_b32_e32 v115, v2
	v_mov_b32_e32 v116, v2
	v_mov_b32_e32 v117, v2
	v_mov_b32_e32 v118, v2
	v_mov_b32_e32 v119, v2
	v_mov_b32_e32 v120, v2
	v_mov_b32_e32 v121, v2
	v_mov_b32_e32 v74, v2
	v_mov_b32_e32 v75, v2
	v_mov_b32_e32 v76, v2
	v_mov_b32_e32 v77, v2
	v_mov_b32_e32 v78, v2
	v_mov_b32_e32 v79, v2
	v_mov_b32_e32 v80, v2
	v_mov_b32_e32 v81, v2
	v_mov_b32_e32 v90, v2
	v_mov_b32_e32 v91, v2
	v_mov_b32_e32 v92, v2
	v_mov_b32_e32 v93, v2
	v_mov_b32_e32 v94, v2
	v_mov_b32_e32 v95, v2
	v_mov_b32_e32 v96, v2
	v_mov_b32_e32 v97, v2
	v_mov_b32_e32 v106, v2
	v_mov_b32_e32 v107, v2
	v_mov_b32_e32 v108, v2
	v_mov_b32_e32 v109, v2
	v_mov_b32_e32 v110, v2
	v_mov_b32_e32 v111, v2
	v_mov_b32_e32 v112, v2
	v_mov_b32_e32 v113, v2
	v_mov_b32_e32 v122, v2
	v_mov_b32_e32 v123, v2
	v_mov_b32_e32 v124, v2
	v_mov_b32_e32 v125, v2
	v_mov_b32_e32 v126, v2
	v_mov_b32_e32 v127, v2
	v_mov_b32_e32 v128, v2
	v_mov_b32_e32 v129, v2
	.p2align	7
